# MLA loop: LDS stores and next global loads of the staging set spread over slots 16-18 (one piece per MFMA slot) instead of one block; running tile indices instead of recomputed ones
# speedup vs baseline: 1.0113x; 1.0113x over previous
; #define LOADK(t) do { const int kp_ = TILE_KPOS(t); kreg = *(const u32x4*)((const char*)P.K + (size_t)(koff + (unsigned)(kp_ * KPITCH * 2))); if (VAR == 0 && tid < 256) pereg = *(const u32x4*)((const char*)P.KPE + (size_t)(peoff + (unsigned)(kp_ * 64))); } while (0)
; #define LOADV(t) do { const int kp_ = TILE_KPOS(t); vreg = *(const u32x4*)((const char*)P.VT + (size_t)(voff + (unsigned)(kp_ * 2))); } while (0)
; template <int VAR>
; __device__ __forceinline__ void attn_phase(LAS unsigned char* lds, const AttnP P, int vcu, int G, int wave_s) {
;     ...
;         for (int t = 0; t < nt; ++t) {
;             const bool hn = (t + 1 < nt);
;             if (hn) { const int t2 = (t + 2 < nt) ? t + 2 : nt - 1; LOADK(t2); LOADV(t + 1); }
.Lmla_pre1:
	s_or_b64 exec, exec, s[0:1]
	v_lshl_add_u32 v222, s19, 17, v178
	global_load_dwordx4 v[150:153], v222, s[52:53]
	v_lshl_add_u32 v222, s13, 7, v168
	global_load_dwordx4 v[202:205], v222, s[56:57]
	s_add_i32 s0, s10, 4
	s_cmp_ge_i32 s0, s9
	s_cselect_b32 s1, s9, 0
	s_sub_i32 s19, s0, s1
	s_cmp_ge_i32 s19, s9
	s_cselect_b32 s1, s9, 0
	s_sub_i32 s19, s19, s1
	s_and_b64 vcc, exec, s[2:3]
	s_cbranch_vccnz .Lmla_noprio
	s_setprio 1

; template <int VAR>
; __device__ __forceinline__ void attn_phase(LAS unsigned char* lds, const AttnP P, int vcu, int G, int wave_s) {
;     ...
;                 if (ND0 == 6) {
;                     KR1(0); KR1(1); KR1(2); KR1(3); SB();
;                     QK1(0, negm); EX2(pc0, 0, w0.x); KR1(4); SB();
;                     QK1(1, negm); EX2(pc0, 2, w0.y); KR1(5); SB();
;                     QK1(2, pn0); EX2(pc0, 4, w0.z); KR1(6); SB();
;                     QK1(3, pn1); EX2(pc0, 6, w0.w); KR1(7); SB();
;                     QK1(4, pn0); EX2(pc0, 8, w1.x); KR1(8); SB();
;                     QK1(5, pn1); EX2(pc0, 10, w1.y); KR1(9); SB();
;                     QK1(6, pn0); EX2(pc0, 12, w1.z); KR1(10); SB();
;                     QK1(7, pn1); EX2(pc0, 14, w1.w); KR1(11); SB();
;                     QK1(8, pn0); EX2(pc1, 0, w2.x); VR1(0); SB();
;                     QK1(9, pn1); EX2(pc1, 2, w2.y); VR1(1); SB();
;                     QK1(10, pn0); EX2(pc1, 4, w2.z); VR1(2); SB();
;                     QK1(11, pn1); EX2(pc1, 6, w2.w); VR1(3); SB();
;                 } else {
;                     KR1(0); KR1(1); KR1(2); KR1(3); SB();
;                     QK1(0, negm); EX2(pc0, 0, w0.x); EX2(pc0, 2, w0.y); KR1(4); SB();
;                     QK1(1, negm); EX2(pc0, 4, w0.z); EX2(pc0, 6, w0.w); KR1(5); SB();
;                     QK1(2, pn0); EX2(pc0, 8, w1.x); EX2(pc0, 10, w1.y); KR1(6); SB();
;                     QK1(3, pn1); EX2(pc0, 12, w1.z); EX2(pc0, 14, w1.w); KR1(7); SB();
;                     QK1(4, pn0); EX2(pc1, 0, w2.x); VR1(0); SB();
;                     QK1(5, pn1); EX2(pc1, 2, w2.y); VR1(1); SB();
;                     QK1(6, pn0); EX2(pc1, 4, w2.z); VR1(2); SB();
;                     QK1(7, pn1); EX2(pc1, 6, w2.w); VR1(3); SB();
;                 }
;                 PV1(0, w0); EX2(pc1, 8, w3.x); VR1(4); SB();
;                 PV1(1, w0); EX2(pc1, 10, w3.y); VR1(5); SB();
;                 PV1(2, w1); EX2(pc1, 12, w3.z); VR1(6); SB();
;                 PV1(3, w1); EX2(pc1, 14, w3.w); VR1(7); SB();
;                 lrun += sacc;
;                 PV1(4, w2); MASK_TILE(pn0, pn1, t + 1); SB();
;                 PV1(5, w2); SB();
;                 PV1(6, w3); SB();
;                 PV1(7, w3); rmn = rowmax32(pn0, pn1); if (!USE_NEGM) rmn -= mref; SB();
;     ...
;             if (hn) { STOREK(t & 1); STOREV((t + 1) & 1); }
;             __syncthreads();
.Lmla_p0_go:
	v_exp_f32_e32 v222, v34
	v_exp_f32_e32 v223, v35
	v_add_f32_e32 v164, 0, v222
	v_cvt_pk_bf16_f32 v206, v222, v223
	v_add_f32_e32 v164, v223, v164
	v_exp_f32_e32 v224, v36
	v_exp_f32_e32 v225, v37
	v_add_f32_e32 v164, v224, v164
	v_cvt_pk_bf16_f32 v207, v224, v225
	v_add_f32_e32 v164, v225, v164
	s_waitcnt lgkmcnt(3)
	v_mfma_f32_32x32x16_bf16 v[82:97], v[182:185], v[114:117], v[66:81]
	ds_read_b128 v[198:201], v174 offset:22592
	v_exp_f32_e32 v222, v38
	v_exp_f32_e32 v223, v39
	v_add_f32_e32 v164, v222, v164
	v_cvt_pk_bf16_f32 v208, v222, v223
	v_add_f32_e32 v164, v223, v164
	s_waitcnt lgkmcnt(3)
	v_mfma_f32_32x32x16_bf16 v[98:113], v[186:189], v[114:117], v[66:81]
	ds_read_b128 v[182:185], v174 offset:29248
	v_exp_f32_e32 v224, v40
	v_exp_f32_e32 v225, v41
	v_add_f32_e32 v164, v224, v164
	v_cvt_pk_bf16_f32 v209, v224, v225
	v_add_f32_e32 v164, v225, v164
	s_waitcnt lgkmcnt(3)
	v_mfma_f32_32x32x16_bf16 v[82:97], v[190:193], v[118:121], v[82:97]
	ds_read_b128 v[186:189], v174 offset:22624
	v_exp_f32_e32 v222, v42
	v_exp_f32_e32 v223, v43
	v_add_f32_e32 v164, v222, v164
	v_cvt_pk_bf16_f32 v210, v222, v223
	v_add_f32_e32 v164, v223, v164
	s_waitcnt lgkmcnt(3)
	v_mfma_f32_32x32x16_bf16 v[98:113], v[194:197], v[118:121], v[98:113]
	ds_read_b128 v[190:193], v174 offset:29280
	v_exp_f32_e32 v224, v44
	v_exp_f32_e32 v225, v45
	v_add_f32_e32 v164, v224, v164
	v_cvt_pk_bf16_f32 v211, v224, v225
	v_add_f32_e32 v164, v225, v164
	s_waitcnt lgkmcnt(3)
	v_mfma_f32_32x32x16_bf16 v[82:97], v[198:201], v[122:125], v[82:97]
	ds_read_b128 v[194:197], v174 offset:22656
	v_exp_f32_e32 v222, v46
	v_exp_f32_e32 v223, v47
	v_add_f32_e32 v164, v222, v164
	v_cvt_pk_bf16_f32 v212, v222, v223
	v_add_f32_e32 v164, v223, v164
	s_waitcnt lgkmcnt(3)
	v_mfma_f32_32x32x16_bf16 v[98:113], v[182:185], v[122:125], v[98:113]
	ds_read_b128 v[198:201], v174 offset:29312
	v_exp_f32_e32 v224, v48
	v_exp_f32_e32 v225, v49
	v_add_f32_e32 v164, v224, v164
	v_cvt_pk_bf16_f32 v213, v224, v225
	v_add_f32_e32 v164, v225, v164
	s_waitcnt lgkmcnt(3)
	v_mfma_f32_32x32x16_bf16 v[82:97], v[186:189], v[126:129], v[82:97]
	ds_read_b128 v[182:185], v174 offset:22688
	v_exp_f32_e32 v222, v50
	v_exp_f32_e32 v223, v51
	v_add_f32_e32 v164, v222, v164
	v_cvt_pk_bf16_f32 v214, v222, v223
	v_add_f32_e32 v164, v223, v164
	s_waitcnt lgkmcnt(3)
	v_mfma_f32_32x32x16_bf16 v[98:113], v[190:193], v[126:129], v[98:113]
	ds_read_b128 v[186:189], v174 offset:29344
	v_exp_f32_e32 v224, v52
	v_exp_f32_e32 v225, v53
	v_add_f32_e32 v164, v224, v164
	v_cvt_pk_bf16_f32 v215, v224, v225
	v_add_f32_e32 v164, v225, v164
	s_waitcnt lgkmcnt(3)
	v_mfma_f32_32x32x16_bf16 v[82:97], v[194:197], v[130:133], v[82:97]
	ds_read_b128 v[190:193], v228 offset:13312
	v_exp_f32_e32 v222, v54
	v_exp_f32_e32 v223, v55
	v_add_f32_e32 v164, v222, v164
	v_cvt_pk_bf16_f32 v216, v222, v223
	v_add_f32_e32 v164, v223, v164
	s_waitcnt lgkmcnt(3)
	v_mfma_f32_32x32x16_bf16 v[98:113], v[198:201], v[130:133], v[98:113]
	ds_read_b128 v[194:197], v228 offset:17920
	v_exp_f32_e32 v224, v56
	v_exp_f32_e32 v225, v57
	v_add_f32_e32 v164, v224, v164
	v_cvt_pk_bf16_f32 v217, v224, v225
	v_add_f32_e32 v164, v225, v164
	s_waitcnt lgkmcnt(3)
	v_mfma_f32_32x32x16_bf16 v[82:97], v[182:185], v[134:137], v[82:97]
	ds_read_b128 v[198:201], v228 offset:13344
	v_exp_f32_e32 v222, v58
	v_exp_f32_e32 v223, v59
	v_add_f32_e32 v164, v222, v164
	v_cvt_pk_bf16_f32 v218, v222, v223
	v_add_f32_e32 v164, v223, v164
	s_waitcnt lgkmcnt(3)
	v_mfma_f32_32x32x16_bf16 v[98:113], v[186:189], v[134:137], v[98:113]
	ds_read_b128 v[182:185], v228 offset:17952
	v_exp_f32_e32 v224, v60
	v_exp_f32_e32 v225, v61
	v_add_f32_e32 v164, v224, v164
	v_cvt_pk_bf16_f32 v219, v224, v225
	v_add_f32_e32 v164, v225, v164
	s_waitcnt lgkmcnt(3)
	v_mfma_f32_32x32x16_bf16 v[2:17], v[190:193], v[206:209], v[2:17]
	ds_read_b128 v[186:189], v228 offset:13376
	v_exp_f32_e32 v222, v62
	v_exp_f32_e32 v223, v63
	v_add_f32_e32 v164, v222, v164
	v_cvt_pk_bf16_f32 v220, v222, v223
	v_add_f32_e32 v164, v223, v164
	s_waitcnt lgkmcnt(3)
	v_mfma_f32_32x32x16_bf16 v[18:33], v[194:197], v[206:209], v[18:33]
	ds_read_b128 v[190:193], v228 offset:17984
	v_exp_f32_e32 v224, v64
	v_exp_f32_e32 v225, v65
	v_add_f32_e32 v164, v224, v164
	v_cvt_pk_bf16_f32 v221, v224, v225
	v_add_f32_e32 v164, v225, v164
	s_waitcnt lgkmcnt(3)
	v_mfma_f32_32x32x16_bf16 v[2:17], v[198:201], v[210:213], v[2:17]
	ds_read_b128 v[194:197], v228 offset:13408
	v_max3_f32 v224, v82, v83, v84
	v_max3_f32 v225, v98, v99, v100
	v_max3_f32 v224, v224, v85, v86
	s_waitcnt lgkmcnt(3)
	v_mfma_f32_32x32x16_bf16 v[18:33], v[182:185], v[210:213], v[18:33]
	ds_read_b128 v[198:201], v228 offset:18016
	v_max3_f32 v225, v225, v101, v102
	v_max3_f32 v224, v224, v87, v88
	v_max3_f32 v225, v225, v103, v104
	s_mov_b32 s13, s19
	s_add_i32 s19, s19, 1
	s_cmp_eq_u32 s19, s9
	s_cselect_b32 s19, 0, s19
	s_waitcnt lgkmcnt(3)
	v_mfma_f32_32x32x16_bf16 v[2:17], v[186:189], v[214:217], v[2:17]
	ds_read_b128 v[182:185], v229
	v_max3_f32 v224, v224, v89, v90
	v_max3_f32 v225, v225, v105, v106
	v_max3_f32 v224, v224, v91, v92
	s_waitcnt vmcnt(2)
	v_add_u32_e32 v222, 0xb000, v172
	ds_write_b128 v222, v[146:149] offset:22528
	v_lshl_add_u32 v222, s19, 17, v178
	global_load_dwordx4 v[146:149], v222, s[52:53]
	s_waitcnt lgkmcnt(4)
	v_mfma_f32_32x32x16_bf16 v[18:33], v[190:193], v[214:217], v[18:33]
	ds_read_b128 v[186:189], v229 offset:6656
	v_max3_f32 v225, v225, v107, v108
	v_max3_f32 v224, v224, v93, v94
	v_max3_f32 v225, v225, v109, v110
	s_and_b64 vcc, exec, s[2:3]
	s_cbranch_vccz .Lmla_p0_nope
	v_add_u32_e32 v222, 0xb000, v176
	ds_write_b128 v222, v[138:141] offset:22656
	v_lshl_add_u32 v222, s19, 12, v179
	global_load_dwordx4 v[138:141], v222, s[62:63]
.Lmla_p0_nope:
	s_waitcnt lgkmcnt(4)
	v_mfma_f32_32x32x16_bf16 v[2:17], v[194:197], v[218:221], v[2:17]
	ds_read_b128 v[190:193], v229 offset:32
	v_max3_f32 v224, v224, v95, v96
	v_max3_f32 v225, v225, v111, v112
	ds_write_b128 v173, v[142:145] offset:58368
	v_lshl_add_u32 v222, s13, 7, v168
	global_load_dwordx4 v[142:145], v222, s[56:57]
	s_waitcnt lgkmcnt(5)
	v_mfma_f32_32x32x16_bf16 v[18:33], v[198:201], v[218:221], v[18:33]
	ds_read_b128 v[194:197], v229 offset:6688
	v_max3_f32 v224, v224, v97, v113
	v_max_f32_e32 v224, v224, v225
	v_mov_b32_e32 v225, v224
	v_add_f32_e32 v1, v1, v164
	s_add_i32 s11, s11, 1
	s_nop 0
	v_permlane32_swap_b32_e32 v224, v225
	s_cmp_eq_u32 s9, s11
	v_max_f32_e32 v167, v224, v225
	s_waitcnt lgkmcnt(1)
	s_barrier
	s_cbranch_scc1 .Lmla_exit_p0

; template <int VAR>
; __device__ __forceinline__ void attn_phase(LAS unsigned char* lds, const AttnP P, int vcu, int G, int wave_s) {
;     ...
;                 if (ND0 == 6) {
;                     KR1(0); KR1(1); KR1(2); KR1(3); SB();
;                     QK1(0, negm); EX2(pc0, 0, w0.x); KR1(4); SB();
;                     QK1(1, negm); EX2(pc0, 2, w0.y); KR1(5); SB();
;                     QK1(2, pn0); EX2(pc0, 4, w0.z); KR1(6); SB();
;                     QK1(3, pn1); EX2(pc0, 6, w0.w); KR1(7); SB();
;                     QK1(4, pn0); EX2(pc0, 8, w1.x); KR1(8); SB();
;                     QK1(5, pn1); EX2(pc0, 10, w1.y); KR1(9); SB();
;                     QK1(6, pn0); EX2(pc0, 12, w1.z); KR1(10); SB();
;                     QK1(7, pn1); EX2(pc0, 14, w1.w); KR1(11); SB();
;                     QK1(8, pn0); EX2(pc1, 0, w2.x); VR1(0); SB();
;                     QK1(9, pn1); EX2(pc1, 2, w2.y); VR1(1); SB();
;                     QK1(10, pn0); EX2(pc1, 4, w2.z); VR1(2); SB();
;                     QK1(11, pn1); EX2(pc1, 6, w2.w); VR1(3); SB();
;                 } else {
;                     KR1(0); KR1(1); KR1(2); KR1(3); SB();
;                     QK1(0, negm); EX2(pc0, 0, w0.x); EX2(pc0, 2, w0.y); KR1(4); SB();
;                     QK1(1, negm); EX2(pc0, 4, w0.z); EX2(pc0, 6, w0.w); KR1(5); SB();
;                     QK1(2, pn0); EX2(pc0, 8, w1.x); EX2(pc0, 10, w1.y); KR1(6); SB();
;                     QK1(3, pn1); EX2(pc0, 12, w1.z); EX2(pc0, 14, w1.w); KR1(7); SB();
;                     QK1(4, pn0); EX2(pc1, 0, w2.x); VR1(0); SB();
;                     QK1(5, pn1); EX2(pc1, 2, w2.y); VR1(1); SB();
;                     QK1(6, pn0); EX2(pc1, 4, w2.z); VR1(2); SB();
;                     QK1(7, pn1); EX2(pc1, 6, w2.w); VR1(3); SB();
;                 }
;                 PV1(0, w0); EX2(pc1, 8, w3.x); VR1(4); SB();
;                 PV1(1, w0); EX2(pc1, 10, w3.y); VR1(5); SB();
;                 PV1(2, w1); EX2(pc1, 12, w3.z); VR1(6); SB();
;                 PV1(3, w1); EX2(pc1, 14, w3.w); VR1(7); SB();
;                 lrun += sacc;
;                 PV1(4, w2); MASK_TILE(pn0, pn1, t + 1); SB();
;                 PV1(5, w2); SB();
;                 PV1(6, w3); SB();
;                 PV1(7, w3); rmn = rowmax32(pn0, pn1); if (!USE_NEGM) rmn -= mref; SB();
;     ...
;             if (hn) { STOREK(t & 1); STOREV((t + 1) & 1); }
;             __syncthreads();
.Lmla_p1_go:
	v_exp_f32_e32 v222, v82
	v_exp_f32_e32 v223, v83
	v_add_f32_e32 v164, 0, v222
	v_cvt_pk_bf16_f32 v206, v222, v223
	v_add_f32_e32 v164, v223, v164
	v_exp_f32_e32 v224, v84
	v_exp_f32_e32 v225, v85
	v_add_f32_e32 v164, v224, v164
	v_cvt_pk_bf16_f32 v207, v224, v225
	v_add_f32_e32 v164, v225, v164
	s_waitcnt lgkmcnt(3)
	v_mfma_f32_32x32x16_bf16 v[34:49], v[182:185], v[114:117], v[66:81]
	ds_read_b128 v[198:201], v229 offset:64
	v_exp_f32_e32 v222, v86
	v_exp_f32_e32 v223, v87
	v_add_f32_e32 v164, v222, v164
	v_cvt_pk_bf16_f32 v208, v222, v223
	v_add_f32_e32 v164, v223, v164
	s_waitcnt lgkmcnt(3)
	v_mfma_f32_32x32x16_bf16 v[50:65], v[186:189], v[114:117], v[66:81]
	ds_read_b128 v[182:185], v229 offset:6720
	v_exp_f32_e32 v224, v88
	v_exp_f32_e32 v225, v89
	v_add_f32_e32 v164, v224, v164
	v_cvt_pk_bf16_f32 v209, v224, v225
	v_add_f32_e32 v164, v225, v164
	s_waitcnt lgkmcnt(3)
	v_mfma_f32_32x32x16_bf16 v[34:49], v[190:193], v[118:121], v[34:49]
	ds_read_b128 v[186:189], v229 offset:96
	v_exp_f32_e32 v222, v90
	v_exp_f32_e32 v223, v91
	v_add_f32_e32 v164, v222, v164
	v_cvt_pk_bf16_f32 v210, v222, v223
	v_add_f32_e32 v164, v223, v164
	s_waitcnt lgkmcnt(3)
	v_mfma_f32_32x32x16_bf16 v[50:65], v[194:197], v[118:121], v[50:65]
	ds_read_b128 v[190:193], v229 offset:6752
	v_exp_f32_e32 v224, v92
	v_exp_f32_e32 v225, v93
	v_add_f32_e32 v164, v224, v164
	v_cvt_pk_bf16_f32 v211, v224, v225
	v_add_f32_e32 v164, v225, v164
	s_waitcnt lgkmcnt(3)
	v_mfma_f32_32x32x16_bf16 v[34:49], v[198:201], v[122:125], v[34:49]
	ds_read_b128 v[194:197], v229 offset:128
	v_exp_f32_e32 v222, v94
	v_exp_f32_e32 v223, v95
	v_add_f32_e32 v164, v222, v164
	v_cvt_pk_bf16_f32 v212, v222, v223
	v_add_f32_e32 v164, v223, v164
	s_waitcnt lgkmcnt(3)
	v_mfma_f32_32x32x16_bf16 v[50:65], v[182:185], v[122:125], v[50:65]
	ds_read_b128 v[198:201], v229 offset:6784
	v_exp_f32_e32 v224, v96
	v_exp_f32_e32 v225, v97
	v_add_f32_e32 v164, v224, v164
	v_cvt_pk_bf16_f32 v213, v224, v225
	v_add_f32_e32 v164, v225, v164
	s_waitcnt lgkmcnt(3)
	v_mfma_f32_32x32x16_bf16 v[34:49], v[186:189], v[126:129], v[34:49]
	ds_read_b128 v[182:185], v229 offset:160
	v_exp_f32_e32 v222, v98
	v_exp_f32_e32 v223, v99
	v_add_f32_e32 v164, v222, v164
	v_cvt_pk_bf16_f32 v214, v222, v223
	v_add_f32_e32 v164, v223, v164
	s_waitcnt lgkmcnt(3)
	v_mfma_f32_32x32x16_bf16 v[50:65], v[190:193], v[126:129], v[50:65]
	ds_read_b128 v[186:189], v229 offset:6816
	v_exp_f32_e32 v224, v100
	v_exp_f32_e32 v225, v101
	v_add_f32_e32 v164, v224, v164
	v_cvt_pk_bf16_f32 v215, v224, v225
	v_add_f32_e32 v164, v225, v164
	s_waitcnt lgkmcnt(3)
	v_mfma_f32_32x32x16_bf16 v[34:49], v[194:197], v[130:133], v[34:49]
	ds_read_b128 v[190:193], v228 offset:35840
	v_exp_f32_e32 v222, v102
	v_exp_f32_e32 v223, v103
	v_add_f32_e32 v164, v222, v164
	v_cvt_pk_bf16_f32 v216, v222, v223
	v_add_f32_e32 v164, v223, v164
	s_waitcnt lgkmcnt(3)
	v_mfma_f32_32x32x16_bf16 v[50:65], v[198:201], v[130:133], v[50:65]
	ds_read_b128 v[194:197], v228 offset:40448
	v_exp_f32_e32 v224, v104
	v_exp_f32_e32 v225, v105
	v_add_f32_e32 v164, v224, v164
	v_cvt_pk_bf16_f32 v217, v224, v225
	v_add_f32_e32 v164, v225, v164
	s_waitcnt lgkmcnt(3)
	v_mfma_f32_32x32x16_bf16 v[34:49], v[182:185], v[134:137], v[34:49]
	ds_read_b128 v[198:201], v228 offset:35872
	v_exp_f32_e32 v222, v106
	v_exp_f32_e32 v223, v107
	v_add_f32_e32 v164, v222, v164
	v_cvt_pk_bf16_f32 v218, v222, v223
	v_add_f32_e32 v164, v223, v164
	s_waitcnt lgkmcnt(3)
	v_mfma_f32_32x32x16_bf16 v[50:65], v[186:189], v[134:137], v[50:65]
	ds_read_b128 v[182:185], v228 offset:40480
	v_exp_f32_e32 v224, v108
	v_exp_f32_e32 v225, v109
	v_add_f32_e32 v164, v224, v164
	v_cvt_pk_bf16_f32 v219, v224, v225
	v_add_f32_e32 v164, v225, v164
	s_waitcnt lgkmcnt(3)
	v_mfma_f32_32x32x16_bf16 v[2:17], v[190:193], v[206:209], v[2:17]
	ds_read_b128 v[186:189], v228 offset:35904
	v_exp_f32_e32 v222, v110
	v_exp_f32_e32 v223, v111
	v_add_f32_e32 v164, v222, v164
	v_cvt_pk_bf16_f32 v220, v222, v223
	v_add_f32_e32 v164, v223, v164
	s_waitcnt lgkmcnt(3)
	v_mfma_f32_32x32x16_bf16 v[18:33], v[194:197], v[206:209], v[18:33]
	ds_read_b128 v[190:193], v228 offset:40512
	v_exp_f32_e32 v224, v112
	v_exp_f32_e32 v225, v113
	v_add_f32_e32 v164, v224, v164
	v_cvt_pk_bf16_f32 v221, v224, v225
	v_add_f32_e32 v164, v225, v164
	s_waitcnt lgkmcnt(3)
	v_mfma_f32_32x32x16_bf16 v[2:17], v[198:201], v[210:213], v[2:17]
	ds_read_b128 v[194:197], v228 offset:35936
	v_max3_f32 v224, v34, v35, v36
	v_max3_f32 v225, v50, v51, v52
	v_max3_f32 v224, v224, v37, v38
	s_waitcnt lgkmcnt(3)
	v_mfma_f32_32x32x16_bf16 v[18:33], v[182:185], v[210:213], v[18:33]
	ds_read_b128 v[198:201], v228 offset:40544
	v_max3_f32 v225, v225, v53, v54
	v_max3_f32 v224, v224, v39, v40
	v_max3_f32 v225, v225, v55, v56
	s_mov_b32 s13, s19
	s_add_i32 s19, s19, 1
	s_cmp_eq_u32 s19, s9
	s_cselect_b32 s19, 0, s19
	s_waitcnt lgkmcnt(3)
	v_mfma_f32_32x32x16_bf16 v[2:17], v[186:189], v[214:217], v[2:17]
	ds_read_b128 v[182:185], v229 offset:22528
	v_max3_f32 v224, v224, v41, v42
	v_max3_f32 v225, v225, v57, v58
	v_max3_f32 v224, v224, v43, v44
	s_waitcnt vmcnt(2)
	ds_write_b128 v172, v[150:153]
	v_lshl_add_u32 v222, s19, 17, v178
	global_load_dwordx4 v[150:153], v222, s[52:53]
	s_waitcnt lgkmcnt(4)
	v_mfma_f32_32x32x16_bf16 v[18:33], v[190:193], v[214:217], v[18:33]
	ds_read_b128 v[186:189], v229 offset:29184
	v_max3_f32 v225, v225, v59, v60
	v_max3_f32 v224, v224, v45, v46
	v_max3_f32 v225, v225, v61, v62
	s_and_b64 vcc, exec, s[2:3]
	s_cbranch_vccz .Lmla_p1_nope
	ds_write_b128 v176, v[160:163] offset:128
	v_lshl_add_u32 v222, s19, 12, v179
	global_load_dwordx4 v[160:163], v222, s[62:63]
.Lmla_p1_nope:
	s_waitcnt lgkmcnt(4)
	v_mfma_f32_32x32x16_bf16 v[2:17], v[194:197], v[218:221], v[2:17]
	ds_read_b128 v[190:193], v229 offset:22560
	v_max3_f32 v224, v224, v47, v48
	v_max3_f32 v225, v225, v63, v64
	v_add_u32_e32 v222, 0xb000, v173
	ds_write_b128 v222, v[202:205] offset:35840
	v_lshl_add_u32 v222, s13, 7, v168
	global_load_dwordx4 v[202:205], v222, s[56:57]
	s_waitcnt lgkmcnt(5)
	v_mfma_f32_32x32x16_bf16 v[18:33], v[198:201], v[218:221], v[18:33]
	ds_read_b128 v[194:197], v229 offset:29216
	v_max3_f32 v224, v224, v49, v65
	v_max_f32_e32 v224, v224, v225
	v_mov_b32_e32 v225, v224
	v_add_f32_e32 v1, v1, v164
	s_add_i32 s11, s11, 1
	s_nop 0
	v_permlane32_swap_b32_e32 v224, v225
	s_cmp_eq_u32 s9, s11
	v_max_f32_e32 v167, v224, v225
	s_waitcnt lgkmcnt(1)
	s_barrier
	s_cbranch_scc1 .Lmla_exit_p1

; template <int VAR>
; __device__ __forceinline__ void attn_phase(LAS unsigned char* lds, const AttnP P, int vcu, int G, int wave_s) {
;     ...
;                 if (ND0 == 6) {
;                     KR1(0); KR1(1); KR1(2); KR1(3); SB();
;                     QK1(0, negm); EX2(pc0, 0, w0.x); KR1(4); SB();
;                     QK1(1, negm); EX2(pc0, 2, w0.y); KR1(5); SB();
;                     QK1(2, pn0); EX2(pc0, 4, w0.z); KR1(6); SB();
;                     QK1(3, pn1); EX2(pc0, 6, w0.w); KR1(7); SB();
;                     QK1(4, pn0); EX2(pc0, 8, w1.x); KR1(8); SB();
;                     QK1(5, pn1); EX2(pc0, 10, w1.y); KR1(9); SB();
;                     QK1(6, pn0); EX2(pc0, 12, w1.z); KR1(10); SB();
;                     QK1(7, pn1); EX2(pc0, 14, w1.w); KR1(11); SB();
;                     QK1(8, pn0); EX2(pc1, 0, w2.x); VR1(0); SB();
;                     QK1(9, pn1); EX2(pc1, 2, w2.y); VR1(1); SB();
;                     QK1(10, pn0); EX2(pc1, 4, w2.z); VR1(2); SB();
;                     QK1(11, pn1); EX2(pc1, 6, w2.w); VR1(3); SB();
;                 } else {
;                     KR1(0); KR1(1); KR1(2); KR1(3); SB();
;                     QK1(0, negm); EX2(pc0, 0, w0.x); EX2(pc0, 2, w0.y); KR1(4); SB();
;                     QK1(1, negm); EX2(pc0, 4, w0.z); EX2(pc0, 6, w0.w); KR1(5); SB();
;                     QK1(2, pn0); EX2(pc0, 8, w1.x); EX2(pc0, 10, w1.y); KR1(6); SB();
;                     QK1(3, pn1); EX2(pc0, 12, w1.z); EX2(pc0, 14, w1.w); KR1(7); SB();
;                     QK1(4, pn0); EX2(pc1, 0, w2.x); VR1(0); SB();
;                     QK1(5, pn1); EX2(pc1, 2, w2.y); VR1(1); SB();
;                     QK1(6, pn0); EX2(pc1, 4, w2.z); VR1(2); SB();
;                     QK1(7, pn1); EX2(pc1, 6, w2.w); VR1(3); SB();
;                 }
;                 PV1(0, w0); EX2(pc1, 8, w3.x); VR1(4); SB();
;                 PV1(1, w0); EX2(pc1, 10, w3.y); VR1(5); SB();
;                 PV1(2, w1); EX2(pc1, 12, w3.z); VR1(6); SB();
;                 PV1(3, w1); EX2(pc1, 14, w3.w); VR1(7); SB();
;                 lrun += sacc;
;                 PV1(4, w2); MASK_TILE(pn0, pn1, t + 1); SB();
;                 PV1(5, w2); SB();
;                 PV1(6, w3); SB();
;                 PV1(7, w3); rmn = rowmax32(pn0, pn1); if (!USE_NEGM) rmn -= mref; SB();
;     ...
;             if (hn) { STOREK(t & 1); STOREV((t + 1) & 1); }
;             __syncthreads();
.Lmla_p2_go:
	v_exp_f32_e32 v222, v34
	v_exp_f32_e32 v223, v35
	v_add_f32_e32 v164, 0, v222
	v_cvt_pk_bf16_f32 v206, v222, v223
	v_add_f32_e32 v164, v223, v164
	v_exp_f32_e32 v224, v36
	v_exp_f32_e32 v225, v37
	v_add_f32_e32 v164, v224, v164
	v_cvt_pk_bf16_f32 v207, v224, v225
	v_add_f32_e32 v164, v225, v164
	s_waitcnt lgkmcnt(3)
	v_mfma_f32_32x32x16_bf16 v[82:97], v[182:185], v[114:117], v[66:81]
	ds_read_b128 v[198:201], v229 offset:22592
	v_exp_f32_e32 v222, v38
	v_exp_f32_e32 v223, v39
	v_add_f32_e32 v164, v222, v164
	v_cvt_pk_bf16_f32 v208, v222, v223
	v_add_f32_e32 v164, v223, v164
	s_waitcnt lgkmcnt(3)
	v_mfma_f32_32x32x16_bf16 v[98:113], v[186:189], v[114:117], v[66:81]
	ds_read_b128 v[182:185], v229 offset:29248
	v_exp_f32_e32 v224, v40
	v_exp_f32_e32 v225, v41
	v_add_f32_e32 v164, v224, v164
	v_cvt_pk_bf16_f32 v209, v224, v225
	v_add_f32_e32 v164, v225, v164
	s_waitcnt lgkmcnt(3)
	v_mfma_f32_32x32x16_bf16 v[82:97], v[190:193], v[118:121], v[82:97]
	ds_read_b128 v[186:189], v229 offset:22624
	v_exp_f32_e32 v222, v42
	v_exp_f32_e32 v223, v43
	v_add_f32_e32 v164, v222, v164
	v_cvt_pk_bf16_f32 v210, v222, v223
	v_add_f32_e32 v164, v223, v164
	s_waitcnt lgkmcnt(3)
	v_mfma_f32_32x32x16_bf16 v[98:113], v[194:197], v[118:121], v[98:113]
	ds_read_b128 v[190:193], v229 offset:29280
	v_exp_f32_e32 v224, v44
	v_exp_f32_e32 v225, v45
	v_add_f32_e32 v164, v224, v164
	v_cvt_pk_bf16_f32 v211, v224, v225
	v_add_f32_e32 v164, v225, v164
	s_waitcnt lgkmcnt(3)
	v_mfma_f32_32x32x16_bf16 v[82:97], v[198:201], v[122:125], v[82:97]
	ds_read_b128 v[194:197], v229 offset:22656
	v_exp_f32_e32 v222, v46
	v_exp_f32_e32 v223, v47
	v_add_f32_e32 v164, v222, v164
	v_cvt_pk_bf16_f32 v212, v222, v223
	v_add_f32_e32 v164, v223, v164
	s_waitcnt lgkmcnt(3)
	v_mfma_f32_32x32x16_bf16 v[98:113], v[182:185], v[122:125], v[98:113]
	ds_read_b128 v[198:201], v229 offset:29312
	v_exp_f32_e32 v224, v48
	v_exp_f32_e32 v225, v49
	v_add_f32_e32 v164, v224, v164
	v_cvt_pk_bf16_f32 v213, v224, v225
	v_add_f32_e32 v164, v225, v164
	s_waitcnt lgkmcnt(3)
	v_mfma_f32_32x32x16_bf16 v[82:97], v[186:189], v[126:129], v[82:97]
	ds_read_b128 v[182:185], v229 offset:22688
	v_exp_f32_e32 v222, v50
	v_exp_f32_e32 v223, v51
	v_add_f32_e32 v164, v222, v164
	v_cvt_pk_bf16_f32 v214, v222, v223
	v_add_f32_e32 v164, v223, v164
	s_waitcnt lgkmcnt(3)
	v_mfma_f32_32x32x16_bf16 v[98:113], v[190:193], v[126:129], v[98:113]
	ds_read_b128 v[186:189], v229 offset:29344
	v_exp_f32_e32 v224, v52
	v_exp_f32_e32 v225, v53
	v_add_f32_e32 v164, v224, v164
	v_cvt_pk_bf16_f32 v215, v224, v225
	v_add_f32_e32 v164, v225, v164
	s_waitcnt lgkmcnt(3)
	v_mfma_f32_32x32x16_bf16 v[82:97], v[194:197], v[130:133], v[82:97]
	ds_read_b128 v[190:193], v181 offset:13312
	v_exp_f32_e32 v222, v54
	v_exp_f32_e32 v223, v55
	v_add_f32_e32 v164, v222, v164
	v_cvt_pk_bf16_f32 v216, v222, v223
	v_add_f32_e32 v164, v223, v164
	s_waitcnt lgkmcnt(3)
	v_mfma_f32_32x32x16_bf16 v[98:113], v[198:201], v[130:133], v[98:113]
	ds_read_b128 v[194:197], v181 offset:17920
	v_exp_f32_e32 v224, v56
	v_exp_f32_e32 v225, v57
	v_add_f32_e32 v164, v224, v164
	v_cvt_pk_bf16_f32 v217, v224, v225
	v_add_f32_e32 v164, v225, v164
	s_waitcnt lgkmcnt(3)
	v_mfma_f32_32x32x16_bf16 v[82:97], v[182:185], v[134:137], v[82:97]
	ds_read_b128 v[198:201], v181 offset:13344
	v_exp_f32_e32 v222, v58
	v_exp_f32_e32 v223, v59
	v_add_f32_e32 v164, v222, v164
	v_cvt_pk_bf16_f32 v218, v222, v223
	v_add_f32_e32 v164, v223, v164
	s_waitcnt lgkmcnt(3)
	v_mfma_f32_32x32x16_bf16 v[98:113], v[186:189], v[134:137], v[98:113]
	ds_read_b128 v[182:185], v181 offset:17952
	v_exp_f32_e32 v224, v60
	v_exp_f32_e32 v225, v61
	v_add_f32_e32 v164, v224, v164
	v_cvt_pk_bf16_f32 v219, v224, v225
	v_add_f32_e32 v164, v225, v164
	s_waitcnt lgkmcnt(3)
	v_mfma_f32_32x32x16_bf16 v[2:17], v[190:193], v[206:209], v[2:17]
	ds_read_b128 v[186:189], v181 offset:13376
	v_exp_f32_e32 v222, v62
	v_exp_f32_e32 v223, v63
	v_add_f32_e32 v164, v222, v164
	v_cvt_pk_bf16_f32 v220, v222, v223
	v_add_f32_e32 v164, v223, v164
	s_waitcnt lgkmcnt(3)
	v_mfma_f32_32x32x16_bf16 v[18:33], v[194:197], v[206:209], v[18:33]
	ds_read_b128 v[190:193], v181 offset:17984
	v_exp_f32_e32 v224, v64
	v_exp_f32_e32 v225, v65
	v_add_f32_e32 v164, v224, v164
	v_cvt_pk_bf16_f32 v221, v224, v225
	v_add_f32_e32 v164, v225, v164
	s_waitcnt lgkmcnt(3)
	v_mfma_f32_32x32x16_bf16 v[2:17], v[198:201], v[210:213], v[2:17]
	ds_read_b128 v[194:197], v181 offset:13408
	v_max3_f32 v224, v82, v83, v84
	v_max3_f32 v225, v98, v99, v100
	v_max3_f32 v224, v224, v85, v86
	s_waitcnt lgkmcnt(3)
	v_mfma_f32_32x32x16_bf16 v[18:33], v[182:185], v[210:213], v[18:33]
	ds_read_b128 v[198:201], v181 offset:18016
	v_max3_f32 v225, v225, v101, v102
	v_max3_f32 v224, v224, v87, v88
	v_max3_f32 v225, v225, v103, v104
	s_mov_b32 s13, s19
	s_add_i32 s19, s19, 1
	s_cmp_eq_u32 s19, s9
	s_cselect_b32 s19, 0, s19
	s_waitcnt lgkmcnt(3)
	v_mfma_f32_32x32x16_bf16 v[2:17], v[186:189], v[214:217], v[2:17]
	ds_read_b128 v[182:185], v174
	v_max3_f32 v224, v224, v89, v90
	v_max3_f32 v225, v225, v105, v106
	v_max3_f32 v224, v224, v91, v92
	s_waitcnt vmcnt(2)
	ds_write_b128 v172, v[146:149] offset:22528
	v_lshl_add_u32 v222, s19, 17, v178
	global_load_dwordx4 v[146:149], v222, s[52:53]
	s_waitcnt lgkmcnt(4)
	v_mfma_f32_32x32x16_bf16 v[18:33], v[190:193], v[214:217], v[18:33]
	ds_read_b128 v[186:189], v174 offset:6656
	v_max3_f32 v225, v225, v107, v108
	v_max3_f32 v224, v224, v93, v94
	v_max3_f32 v225, v225, v109, v110
	s_and_b64 vcc, exec, s[2:3]
	s_cbranch_vccz .Lmla_p2_nope
	ds_write_b128 v176, v[138:141] offset:22656
	v_lshl_add_u32 v222, s19, 12, v179
	global_load_dwordx4 v[138:141], v222, s[62:63]
.Lmla_p2_nope:
	s_waitcnt lgkmcnt(4)
	v_mfma_f32_32x32x16_bf16 v[2:17], v[194:197], v[218:221], v[2:17]
	ds_read_b128 v[190:193], v174 offset:32
	v_max3_f32 v224, v224, v95, v96
	v_max3_f32 v225, v225, v111, v112
	ds_write_b128 v173, v[142:145] offset:13312
	v_lshl_add_u32 v222, s13, 7, v168
	global_load_dwordx4 v[142:145], v222, s[56:57]
	s_waitcnt lgkmcnt(5)
	v_mfma_f32_32x32x16_bf16 v[18:33], v[198:201], v[218:221], v[18:33]
	ds_read_b128 v[194:197], v174 offset:6688
	v_max3_f32 v224, v224, v97, v113
	v_max_f32_e32 v224, v224, v225
	v_mov_b32_e32 v225, v224
	v_add_f32_e32 v1, v1, v164
	s_add_i32 s11, s11, 1
	s_nop 0
	v_permlane32_swap_b32_e32 v224, v225
	s_cmp_eq_u32 s9, s11
	v_max_f32_e32 v167, v224, v225
	s_waitcnt lgkmcnt(1)
	s_barrier
	s_cbranch_scc1 .Lmla_exit_p2

; template <int VAR>
; __device__ __forceinline__ void attn_phase(LAS unsigned char* lds, const AttnP P, int vcu, int G, int wave_s) {
;     ...
;                 if (ND0 == 6) {
;                     KR1(0); KR1(1); KR1(2); KR1(3); SB();
;                     QK1(0, negm); EX2(pc0, 0, w0.x); KR1(4); SB();
;                     QK1(1, negm); EX2(pc0, 2, w0.y); KR1(5); SB();
;                     QK1(2, pn0); EX2(pc0, 4, w0.z); KR1(6); SB();
;                     QK1(3, pn1); EX2(pc0, 6, w0.w); KR1(7); SB();
;                     QK1(4, pn0); EX2(pc0, 8, w1.x); KR1(8); SB();
;                     QK1(5, pn1); EX2(pc0, 10, w1.y); KR1(9); SB();
;                     QK1(6, pn0); EX2(pc0, 12, w1.z); KR1(10); SB();
;                     QK1(7, pn1); EX2(pc0, 14, w1.w); KR1(11); SB();
;                     QK1(8, pn0); EX2(pc1, 0, w2.x); VR1(0); SB();
;                     QK1(9, pn1); EX2(pc1, 2, w2.y); VR1(1); SB();
;                     QK1(10, pn0); EX2(pc1, 4, w2.z); VR1(2); SB();
;                     QK1(11, pn1); EX2(pc1, 6, w2.w); VR1(3); SB();
;                 } else {
;                     KR1(0); KR1(1); KR1(2); KR1(3); SB();
;                     QK1(0, negm); EX2(pc0, 0, w0.x); EX2(pc0, 2, w0.y); KR1(4); SB();
;                     QK1(1, negm); EX2(pc0, 4, w0.z); EX2(pc0, 6, w0.w); KR1(5); SB();
;                     QK1(2, pn0); EX2(pc0, 8, w1.x); EX2(pc0, 10, w1.y); KR1(6); SB();
;                     QK1(3, pn1); EX2(pc0, 12, w1.z); EX2(pc0, 14, w1.w); KR1(7); SB();
;                     QK1(4, pn0); EX2(pc1, 0, w2.x); VR1(0); SB();
;                     QK1(5, pn1); EX2(pc1, 2, w2.y); VR1(1); SB();
;                     QK1(6, pn0); EX2(pc1, 4, w2.z); VR1(2); SB();
;                     QK1(7, pn1); EX2(pc1, 6, w2.w); VR1(3); SB();
;                 }
;                 PV1(0, w0); EX2(pc1, 8, w3.x); VR1(4); SB();
;                 PV1(1, w0); EX2(pc1, 10, w3.y); VR1(5); SB();
;                 PV1(2, w1); EX2(pc1, 12, w3.z); VR1(6); SB();
;                 PV1(3, w1); EX2(pc1, 14, w3.w); VR1(7); SB();
;                 lrun += sacc;
;                 PV1(4, w2); MASK_TILE(pn0, pn1, t + 1); SB();
;                 PV1(5, w2); SB();
;                 PV1(6, w3); SB();
;                 PV1(7, w3); rmn = rowmax32(pn0, pn1); if (!USE_NEGM) rmn -= mref; SB();
;     ...
;             if (hn) { STOREK(t & 1); STOREV((t + 1) & 1); }
;             __syncthreads();
.Lmla_p3_go:
	v_exp_f32_e32 v222, v82
	v_exp_f32_e32 v223, v83
	v_add_f32_e32 v164, 0, v222
	v_cvt_pk_bf16_f32 v206, v222, v223
	v_add_f32_e32 v164, v223, v164
	v_exp_f32_e32 v224, v84
	v_exp_f32_e32 v225, v85
	v_add_f32_e32 v164, v224, v164
	v_cvt_pk_bf16_f32 v207, v224, v225
	v_add_f32_e32 v164, v225, v164
	s_waitcnt lgkmcnt(3)
	v_mfma_f32_32x32x16_bf16 v[34:49], v[182:185], v[114:117], v[66:81]
	ds_read_b128 v[198:201], v174 offset:64
	v_exp_f32_e32 v222, v86
	v_exp_f32_e32 v223, v87
	v_add_f32_e32 v164, v222, v164
	v_cvt_pk_bf16_f32 v208, v222, v223
	v_add_f32_e32 v164, v223, v164
	s_waitcnt lgkmcnt(3)
	v_mfma_f32_32x32x16_bf16 v[50:65], v[186:189], v[114:117], v[66:81]
	ds_read_b128 v[182:185], v174 offset:6720
	v_exp_f32_e32 v224, v88
	v_exp_f32_e32 v225, v89
	v_add_f32_e32 v164, v224, v164
	v_cvt_pk_bf16_f32 v209, v224, v225
	v_add_f32_e32 v164, v225, v164
	s_waitcnt lgkmcnt(3)
	v_mfma_f32_32x32x16_bf16 v[34:49], v[190:193], v[118:121], v[34:49]
	ds_read_b128 v[186:189], v174 offset:96
	v_exp_f32_e32 v222, v90
	v_exp_f32_e32 v223, v91
	v_add_f32_e32 v164, v222, v164
	v_cvt_pk_bf16_f32 v210, v222, v223
	v_add_f32_e32 v164, v223, v164
	s_waitcnt lgkmcnt(3)
	v_mfma_f32_32x32x16_bf16 v[50:65], v[194:197], v[118:121], v[50:65]
	ds_read_b128 v[190:193], v174 offset:6752
	v_exp_f32_e32 v224, v92
	v_exp_f32_e32 v225, v93
	v_add_f32_e32 v164, v224, v164
	v_cvt_pk_bf16_f32 v211, v224, v225
	v_add_f32_e32 v164, v225, v164
	s_waitcnt lgkmcnt(3)
	v_mfma_f32_32x32x16_bf16 v[34:49], v[198:201], v[122:125], v[34:49]
	ds_read_b128 v[194:197], v174 offset:128
	v_exp_f32_e32 v222, v94
	v_exp_f32_e32 v223, v95
	v_add_f32_e32 v164, v222, v164
	v_cvt_pk_bf16_f32 v212, v222, v223
	v_add_f32_e32 v164, v223, v164
	s_waitcnt lgkmcnt(3)
	v_mfma_f32_32x32x16_bf16 v[50:65], v[182:185], v[122:125], v[50:65]
	ds_read_b128 v[198:201], v174 offset:6784
	v_exp_f32_e32 v224, v96
	v_exp_f32_e32 v225, v97
	v_add_f32_e32 v164, v224, v164
	v_cvt_pk_bf16_f32 v213, v224, v225
	v_add_f32_e32 v164, v225, v164
	s_waitcnt lgkmcnt(3)
	v_mfma_f32_32x32x16_bf16 v[34:49], v[186:189], v[126:129], v[34:49]
	ds_read_b128 v[182:185], v174 offset:160
	v_exp_f32_e32 v222, v98
	v_exp_f32_e32 v223, v99
	v_add_f32_e32 v164, v222, v164
	v_cvt_pk_bf16_f32 v214, v222, v223
	v_add_f32_e32 v164, v223, v164
	s_waitcnt lgkmcnt(3)
	v_mfma_f32_32x32x16_bf16 v[50:65], v[190:193], v[126:129], v[50:65]
	ds_read_b128 v[186:189], v174 offset:6816
	v_exp_f32_e32 v224, v100
	v_exp_f32_e32 v225, v101
	v_add_f32_e32 v164, v224, v164
	v_cvt_pk_bf16_f32 v215, v224, v225
	v_add_f32_e32 v164, v225, v164
	s_waitcnt lgkmcnt(3)
	v_mfma_f32_32x32x16_bf16 v[34:49], v[194:197], v[130:133], v[34:49]
	ds_read_b128 v[190:193], v181 offset:35840
	v_exp_f32_e32 v222, v102
	v_exp_f32_e32 v223, v103
	v_add_f32_e32 v164, v222, v164
	v_cvt_pk_bf16_f32 v216, v222, v223
	v_add_f32_e32 v164, v223, v164
	s_waitcnt lgkmcnt(3)
	v_mfma_f32_32x32x16_bf16 v[50:65], v[198:201], v[130:133], v[50:65]
	ds_read_b128 v[194:197], v181 offset:40448
	v_exp_f32_e32 v224, v104
	v_exp_f32_e32 v225, v105
	v_add_f32_e32 v164, v224, v164
	v_cvt_pk_bf16_f32 v217, v224, v225
	v_add_f32_e32 v164, v225, v164
	s_waitcnt lgkmcnt(3)
	v_mfma_f32_32x32x16_bf16 v[34:49], v[182:185], v[134:137], v[34:49]
	ds_read_b128 v[198:201], v181 offset:35872
	v_exp_f32_e32 v222, v106
	v_exp_f32_e32 v223, v107
	v_add_f32_e32 v164, v222, v164
	v_cvt_pk_bf16_f32 v218, v222, v223
	v_add_f32_e32 v164, v223, v164
	s_waitcnt lgkmcnt(3)
	v_mfma_f32_32x32x16_bf16 v[50:65], v[186:189], v[134:137], v[50:65]
	ds_read_b128 v[182:185], v181 offset:40480
	v_exp_f32_e32 v224, v108
	v_exp_f32_e32 v225, v109
	v_add_f32_e32 v164, v224, v164
	v_cvt_pk_bf16_f32 v219, v224, v225
	v_add_f32_e32 v164, v225, v164
	s_waitcnt lgkmcnt(3)
	v_mfma_f32_32x32x16_bf16 v[2:17], v[190:193], v[206:209], v[2:17]
	ds_read_b128 v[186:189], v181 offset:35904
	v_exp_f32_e32 v222, v110
	v_exp_f32_e32 v223, v111
	v_add_f32_e32 v164, v222, v164
	v_cvt_pk_bf16_f32 v220, v222, v223
	v_add_f32_e32 v164, v223, v164
	s_waitcnt lgkmcnt(3)
	v_mfma_f32_32x32x16_bf16 v[18:33], v[194:197], v[206:209], v[18:33]
	ds_read_b128 v[190:193], v181 offset:40512
	v_exp_f32_e32 v224, v112
	v_exp_f32_e32 v225, v113
	v_add_f32_e32 v164, v224, v164
	v_cvt_pk_bf16_f32 v221, v224, v225
	v_add_f32_e32 v164, v225, v164
	s_waitcnt lgkmcnt(3)
	v_mfma_f32_32x32x16_bf16 v[2:17], v[198:201], v[210:213], v[2:17]
	ds_read_b128 v[194:197], v181 offset:35936
	v_max3_f32 v224, v34, v35, v36
	v_max3_f32 v225, v50, v51, v52
	v_max3_f32 v224, v224, v37, v38
	s_waitcnt lgkmcnt(3)
	v_mfma_f32_32x32x16_bf16 v[18:33], v[182:185], v[210:213], v[18:33]
	ds_read_b128 v[198:201], v181 offset:40544
	v_max3_f32 v225, v225, v53, v54
	v_max3_f32 v224, v224, v39, v40
	v_max3_f32 v225, v225, v55, v56
	s_mov_b32 s13, s19
	s_add_i32 s19, s19, 1
	s_cmp_eq_u32 s19, s9
	s_cselect_b32 s19, 0, s19
	s_waitcnt lgkmcnt(3)
	v_mfma_f32_32x32x16_bf16 v[2:17], v[186:189], v[214:217], v[2:17]
	ds_read_b128 v[182:185], v174 offset:22528
	v_max3_f32 v224, v224, v41, v42
	v_max3_f32 v225, v225, v57, v58
	v_max3_f32 v224, v224, v43, v44
	s_waitcnt vmcnt(2)
	ds_write_b128 v172, v[150:153] offset:45056
	v_lshl_add_u32 v222, s19, 17, v178
	global_load_dwordx4 v[150:153], v222, s[52:53]
	s_waitcnt lgkmcnt(4)
	v_mfma_f32_32x32x16_bf16 v[18:33], v[190:193], v[214:217], v[18:33]
	ds_read_b128 v[186:189], v174 offset:29184
	v_max3_f32 v225, v225, v59, v60
	v_max3_f32 v224, v224, v45, v46
	v_max3_f32 v225, v225, v61, v62
	s_and_b64 vcc, exec, s[2:3]
	s_cbranch_vccz .Lmla_p3_nope
	ds_write_b128 v176, v[160:163] offset:45184
	v_lshl_add_u32 v222, s19, 12, v179
	global_load_dwordx4 v[160:163], v222, s[62:63]
.Lmla_p3_nope:
	s_waitcnt lgkmcnt(4)
	v_mfma_f32_32x32x16_bf16 v[2:17], v[194:197], v[218:221], v[2:17]
	ds_read_b128 v[190:193], v174 offset:22560
	v_max3_f32 v224, v224, v47, v48
	v_max3_f32 v225, v225, v63, v64
	ds_write_b128 v173, v[202:205] offset:35840
	v_lshl_add_u32 v222, s13, 7, v168
	global_load_dwordx4 v[202:205], v222, s[56:57]
	s_waitcnt lgkmcnt(5)
	v_mfma_f32_32x32x16_bf16 v[18:33], v[198:201], v[218:221], v[18:33]
	ds_read_b128 v[194:197], v174 offset:29216
	v_max3_f32 v224, v224, v49, v65
	v_max_f32_e32 v224, v224, v225
	v_mov_b32_e32 v225, v224
	v_add_f32_e32 v1, v1, v164
	s_add_i32 s11, s11, 1
	s_nop 0
	v_permlane32_swap_b32_e32 v224, v225
	s_cmp_eq_u32 s9, s11
	v_max_f32_e32 v167, v224, v225
	s_waitcnt lgkmcnt(1)
	s_barrier
	s_cbranch_scc1 .Lmla_exit_p3
	s_branch .Lmla_p0
